# fp8 in-proj tile order: merge-gate tiles first (round-0 and round-5 tile sets exchanged), query/key tiles last; bf16 rounds reversed
# speedup vs baseline: 1.0022x; 1.0022x over previous
.LBB0_174:
	v_writelane_b32 v251, s52, 24
	s_nop 1
	v_writelane_b32 v251, s53, 25
	v_writelane_b32 v251, s56, 26
	s_nop 1
	v_writelane_b32 v251, s57, 27
	s_or_b64 exec, exec, s[0:1]
	s_add_u32 s47, s24, 0x7480000
	s_addc_u32 s0, s25, 0
	s_add_u32 s42, s24, 0x11100000
	s_addc_u32 s43, s25, 0
	v_writelane_b32 v251, s0, 28
	s_add_u32 s0, s24, 0x9500000
	v_writelane_b32 v251, s0, 29
	s_addc_u32 s0, s25, 0
	v_writelane_b32 v251, s0, 30
	s_add_u32 s0, s24, 0x6c00000
	v_writelane_b32 v251, s0, 31
	s_addc_u32 s0, s25, 0
	v_writelane_b32 v251, s0, 32
	s_lshr_b32 s0, s26, 31
	s_add_i32 s0, s26, s0
	s_ashr_i32 s8, s0, 1
	s_add_i32 s10, s8, s64
	s_add_u32 s0, s24, 0x9700000
	s_addc_u32 s1, s25, 0
	v_writelane_b32 v251, s0, 33
	s_mov_b64 s[52:53], s[84:85]
	s_mov_b64 s[54:55], s[86:87]
	v_writelane_b32 v251, s1, 34
	s_add_u32 s0, s24, 0x9f80000
	s_addc_u32 s1, s25, 0
	s_ashr_i32 s95, s26, 31
	s_add_u32 s40, s24, 0xd100000
	v_writelane_b32 v251, s0, 35
	s_addc_u32 s41, s25, 0
	s_mov_b64 s[44:45], s[76:77]
	v_writelane_b32 v251, s1, 36
	s_add_u32 s0, s24, 0xe100000
	v_writelane_b32 v251, s0, 37
	s_addc_u32 s0, s25, 0
	s_bitcmp0_b32 s26, 0
	v_writelane_b32 v251, s0, 38
	s_cselect_b64 s[0:1], -1, 0
	s_ashr_i32 s3, s26, 1
	s_sub_i32 s9, 0x680, s3
	s_cmpk_lt_i32 s64, 0x680
	s_cselect_b64 s[4:5], -1, 0
	v_writelane_b32 v251, s4, 39
	s_ashr_i32 s3, s64, 31
	s_mov_b32 s7, s3
	v_writelane_b32 v251, s5, 40
	s_lshr_b32 s4, s3, 29
	s_add_i32 s4, s64, s4
	s_ashr_i32 s11, s4, 3
	s_and_b32 s4, s4, -8
	s_sub_i32 s12, s64, s4
	s_add_u32 s36, s24, 0x7500000
	s_addc_u32 s37, s25, 0
	s_cmpk_lt_i32 s64, 0x400
	s_cselect_b64 s[4:5], -1, 0
	s_lshl_b32 s13, s12, 7
	s_add_u32 s16, s24, 0x28100200
	s_addc_u32 s17, s25, 0
	s_add_u32 s18, s24, 0x28100400
	s_addc_u32 s19, s25, 0
	s_add_u32 s88, s24, 0x28100500
	v_writelane_b32 v251, s4, 41
	s_addc_u32 s89, s25, 0
	s_mov_b64 s[58:59], s[90:91]
	v_writelane_b32 v251, s5, 42
	s_add_u32 s4, s24, 0x28100600
	s_addc_u32 s5, s25, 0
	v_writelane_b32 v251, s4, 43
	s_mul_i32 s27, s27, s26
	s_mul_i32 s83, s27, s2
	v_writelane_b32 v251, s5, 44
	s_add_u32 s4, s24, 0x28100700
	s_addc_u32 s5, s25, 0
	v_writelane_b32 v251, s4, 45
	v_mov_b32_e32 v33, 0
	v_mov_b32_e32 v219, 0x358637bd
	v_writelane_b32 v251, s5, 46
	s_add_u32 s4, s24, 0x28100800
	s_addc_u32 s5, s25, 0
	v_writelane_b32 v251, s4, 47
	v_mov_b32_e32 v220, 0x260
	v_mov_b32_e32 v221, 0x7f7f7f7f
	v_writelane_b32 v251, s5, 48
	s_add_u32 s4, s24, 0x28100900
	s_addc_u32 s5, s25, 0
	v_writelane_b32 v251, s4, 49
	v_mov_b32_e32 v223, 0x2000
	v_mov_b32_e32 v224, 1
	v_writelane_b32 v251, s5, 50
	s_add_u32 s4, s24, 0x28100a00
	s_addc_u32 s5, s25, 0
	v_writelane_b32 v251, s4, 51
	v_mov_b32_e32 v225, 0xf149f2ca
	v_mbcnt_hi_u32_b32 v226, -1, v34
	v_writelane_b32 v251, s5, 52
	s_add_u32 s4, s24, 0x28100b00
	s_addc_u32 s5, s25, 0
	v_writelane_b32 v251, s4, 53
	v_mov_b64_e32 v[246:247], 0x100
	v_mov_b64_e32 v[248:249], 0xff
	v_writelane_b32 v251, s5, 54
	s_add_u32 s4, s24, 0x28100c00
	s_addc_u32 s5, s25, 0
	v_writelane_b32 v251, s4, 55
	s_mov_b32 s79, 0x100000
	s_mov_b32 s81, 0x3c800000
	v_writelane_b32 v251, s5, 56
	s_add_u32 s4, s24, 0x28100d00
	s_addc_u32 s5, s25, 0
	v_writelane_b32 v251, s4, 57
	s_movk_i32 s70, 0x5400
	s_mov_b32 s71, 0x3e6d3388
	v_writelane_b32 v251, s5, 58
	s_add_u32 s4, s24, 0x28100e00
	s_addc_u32 s5, s25, 0
	v_writelane_b32 v251, s4, 59
	s_movk_i32 s33, 0x110
	s_mov_b32 s73, 0x3b000000
	v_writelane_b32 v251, s5, 60
	s_add_u32 s4, s24, 0x28100f00
	s_addc_u32 s5, s25, 0
	v_writelane_b32 v251, s4, 61
	s_mov_b32 s82, 0x1000000
	s_mov_b32 s94, 0xfffff
	v_writelane_b32 v251, s5, 62
	s_add_u32 s4, s24, 0x28101000
	s_addc_u32 s5, s25, 0
	v_writelane_b32 v251, s4, 63
	s_mov_b64 s[38:39], 0x80
	s_mov_b32 s78, 0x3e0293ee
	v_writelane_b32 v252, s5, 0
	s_add_u32 s4, s24, 0x28101100
	s_addc_u32 s5, s25, 0
	v_writelane_b32 v252, s4, 1
	s_mov_b32 s80, 0x437f0000
	s_waitcnt lgkmcnt(0)
	v_writelane_b32 v252, s5, 2
	s_add_u32 s4, s24, 0x28101200
	s_addc_u32 s5, s25, 0
	v_writelane_b32 v252, s4, 3
	s_barrier
	s_nop 0
	v_writelane_b32 v252, s5, 4
	s_add_u32 s4, s24, 0x28101300
	s_addc_u32 s5, s25, 0
	v_writelane_b32 v252, s4, 5
	s_nop 1
	v_writelane_b32 v252, s5, 6
	s_add_u32 s4, s24, 0x28103400
	s_addc_u32 s5, s25, 0
	v_writelane_b32 v252, s4, 7
	s_nop 1
	v_writelane_b32 v252, s5, 8
	s_add_u32 s4, s24, 0x28103500
	s_addc_u32 s5, s25, 0
	v_writelane_b32 v252, s4, 9
	s_cmpk_lg_i32 s26, 0x100
	s_nop 0
	v_writelane_b32 v252, s5, 10
	s_cselect_b64 s[4:5], -1, 0
	v_writelane_b32 v252, s4, 11
	s_cmpk_lt_i32 s64, 0xc00
	s_nop 0
	v_writelane_b32 v252, s5, 12
	s_cselect_b64 s[4:5], -1, 0
	v_writelane_b32 v252, s4, 13
	s_add_u32 s3, s24, 0x11102000
	s_nop 0
	v_writelane_b32 v252, s5, 14
	v_writelane_b32 v252, s3, 15
	s_addc_u32 s3, s25, 0
	v_writelane_b32 v252, s3, 16
	s_add_u32 s3, s24, 0x11102400
	v_writelane_b32 v252, s3, 17
	s_addc_u32 s3, s25, 0
	v_writelane_b32 v252, s3, 18
	s_add_u32 s3, s24, 0x11101c00
	v_writelane_b32 v252, s3, 19
	s_addc_u32 s3, s25, 0
	s_add_u32 s4, s24, 0xc100000
	v_writelane_b32 v252, s3, 20
	s_addc_u32 s5, s25, 0
	v_writelane_b32 v252, s4, 21
	s_add_u32 s3, s24, 0x11101800
	s_nop 0
	v_writelane_b32 v252, s5, 22
	v_writelane_b32 v252, s3, 23
	s_addc_u32 s3, s25, 0
	s_add_u32 s4, s24, 0xb100000
	v_writelane_b32 v252, s3, 24
	s_addc_u32 s5, s25, 0
	v_writelane_b32 v252, s4, 25
	s_add_u32 s3, s24, 0x11101400
	s_nop 0
	v_writelane_b32 v252, s5, 26
	v_writelane_b32 v252, s3, 27
	s_addc_u32 s3, s25, 0
	s_add_u32 s22, s24, 0xa100000
	s_addc_u32 s23, s25, 0
	s_add_u32 s68, s24, 0xa000000
	s_addc_u32 s69, s25, 0
	v_writelane_b32 v252, s3, 28
	s_add_u32 s3, s24, 0x7400000
	v_writelane_b32 v252, s3, 29
	s_addc_u32 s3, s25, 0
	v_writelane_b32 v252, s3, 30
	s_add_u32 s3, s24, 0x11100c00
	s_addc_u32 s20, s25, 0
	s_add_u32 s4, s24, 0x11102c00
	v_writelane_b32 v252, s4, 31
	s_addc_u32 s4, s25, 0
	s_bfe_u32 s65, s64, 0x20003
	v_writelane_b32 v252, s4, 32
	s_and_b32 s14, s64, 7
	s_lshl_b32 s4, s65, 9
	s_add_u32 s5, s84, s4
	v_writelane_b32 v252, s5, 33
	s_addc_u32 s5, s85, 0
	v_writelane_b32 v252, s5, 34
	s_add_u32 s4, s86, s4
	v_writelane_b32 v252, s4, 35
	v_writelane_b32 v252, s44, 36
	s_addc_u32 s4, s87, 0
	s_mov_b64 s[84:85], s[18:19]
	v_writelane_b32 v252, s45, 37
	v_writelane_b32 v252, s46, 38
	v_writelane_b32 v252, s47, 39
	v_writelane_b32 v252, s48, 40
	v_writelane_b32 v252, s49, 41
	v_writelane_b32 v252, s50, 42
	v_writelane_b32 v252, s51, 43
	v_writelane_b32 v252, s52, 44
	v_writelane_b32 v252, s53, 45
	v_writelane_b32 v252, s54, 46
	v_writelane_b32 v252, s55, 47
	v_writelane_b32 v252, s56, 48
	v_writelane_b32 v252, s57, 49
	v_writelane_b32 v252, s58, 50
	v_writelane_b32 v252, s59, 51
	v_writelane_b32 v252, s4, 52
	s_lshl_b32 s4, s65, 8
	s_add_u32 s4, s42, s4
	s_addc_u32 s5, s43, 0
	v_writelane_b32 v252, s4, 53
	s_and_b32 s19, s64, 3
	s_mov_b64 s[86:87], s[16:17]
	v_writelane_b32 v252, s5, 54
	s_bfe_u32 s4, s64, 0x10003
	s_bfe_u32 s5, s64, 0x40004
	s_lshl_b32 s6, s4, 11
	s_or_b32 s15, s6, s5
	s_lshr_b32 s5, s64, 1
	s_and_b32 s5, s5, 0x7c
	v_writelane_b32 v252, s5, 55
	s_bfe_u32 s5, s64, 0x10002
	s_cmp_eq_u32 s4, 0
	v_writelane_b32 v252, s5, 56
	s_cselect_b64 s[4:5], -1, 0
	v_writelane_b32 v252, s4, 57
	s_nop 1
	v_writelane_b32 v252, s5, 58
	s_bfe_u32 s4, s64, 0x30003
	s_bfe_u32 s5, s64, 0x20006
	s_lshl_b32 s6, s4, 9
	s_or_b32 s5, s6, s5
	s_add_i32 s6, s15, 0xfffff800
	v_writelane_b32 v252, s15, 59
	s_cmp_eq_u32 s4, 0
	v_writelane_b32 v252, s6, 60
	s_cselect_b64 s[16:17], -1, 0
	s_add_i32 s4, s5, 0xfffffe00
	s_bfe_u32 s6, s64, 0x50003
	v_writelane_b32 v253, s4, 0
	s_lshl_b32 s4, s6, 7
	v_writelane_b32 v252, s16, 61
	v_writelane_b32 v253, s4, 1
	s_addk_i32 s4, 0xff80
	v_writelane_b32 v252, s17, 62
	s_cmp_eq_u32 s6, 0
	v_writelane_b32 v252, s5, 63
	v_writelane_b32 v253, s4, 2
	s_cselect_b64 s[4:5], -1, 0
	v_writelane_b32 v253, s4, 3
	s_nop 1
	v_writelane_b32 v253, s5, 4
	s_lshl_b32 s4, s64, 9
	v_writelane_b32 v253, s4, 5
	s_add_u32 s4, s24, 0x5400000
	v_writelane_b32 v253, s4, 6
	s_addc_u32 s4, s25, 0
	v_writelane_b32 v253, s4, 7
	s_add_u32 s4, s24, 0x11103400
	s_addc_u32 s5, s25, 0
	v_writelane_b32 v253, s4, 8
	s_nop 1
	v_writelane_b32 v253, s5, 9
	s_add_u32 s4, s24, 0x26100000
	s_addc_u32 s5, s25, 0
	s_cmpk_lt_i32 s64, 0x100
	s_cselect_b64 s[16:17], -1, 0
	v_writelane_b32 v253, s16, 10
	s_lshl_b32 s15, s12, 5
	s_add_u32 s6, s24, 0x6400000
	v_writelane_b32 v253, s17, 11
	v_writelane_b32 v253, s6, 12
	s_addc_u32 s6, s25, 0
	v_writelane_b32 v253, s6, 13
	s_cmp_lt_i32 s12, 0
	s_mul_i32 s16, s12, 0x81
	s_movk_i32 s6, 0xd1
	s_cselect_b32 s13, s16, s13
	s_cselect_b32 s16, s6, 0xd0
	s_mul_i32 s16, s12, s16
	s_mul_i32 s12, s12, 33
	s_cselect_b32 s12, s12, s15
	s_add_i32 s16, s16, s11
	s_mul_hi_i32 s15, s16, 0x4ec4ec4f
	s_lshr_b32 s17, s15, 31
	s_ashr_i32 s15, s15, 6
	s_add_i32 s15, s15, s17
	s_mul_i32 s17, s15, 0xd0
	s_sub_i32 s16, s16, s17
	s_bfe_u32 s17, s16, 0x3001c
	s_add_i32 s17, s16, s17
	s_sext_i32_i16 s18, s17
	s_and_b32 s17, s17, 0xfff8
	s_sub_i32 s17, s16, s17
	s_lshl_b32 s15, s15, 3
	s_sext_i32_i16 s17, s17
	s_add_i32 s28, s15, s17
	s_ashr_i32 s15, s18, 3
	s_bfe_u32 s17, s18, 0x100003
	s_cmp_lt_u32 s17, 18
	s_cselect_b32 s17, 12, 16
	s_cmp_gt_i32 s16, 63
	s_cselect_b32 s16, s17, 10
	s_cmp_lt_u32 s15, 4
	s_cselect_b32 s16, 36, s16
	s_sub_u32 s17, s15, 20
	s_cmp_lt_u32 s17, 4
	s_cselect_b32 s16, 0xfffffff6, s16
	s_add_i32 s13, s13, s11
	s_ashr_i32 s17, s13, 31
	s_lshr_b32 s17, s17, 25
	v_writelane_b32 v253, s28, 14
	s_add_i32 s17, s13, s17
	s_and_b32 s18, s17, 0xffffff80
	v_writelane_b32 v253, s29, 15
	s_add_i32 s16, s16, s15
	s_sub_i32 s13, s13, s18
	v_writelane_b32 v253, s16, 16
	s_ashr_i32 s15, s17, 7
	s_lshl_b32 s15, s15, 3
	v_writelane_b32 v253, s17, 17
	s_bfe_i32 s16, s13, 0x80000
	s_bfe_u32 s16, s16, 0x3000c
	s_add_i32 s16, s13, s16
	s_bfe_i32 s17, s16, 0x80000
	s_and_b32 s16, s16, 0xf8
	s_sub_i32 s16, s13, s16
	s_sext_i32_i16 s17, s17
	s_sext_i32_i8 s16, s16
	s_add_i32 s18, s15, s16
	s_ashr_i32 s15, s17, 3
	s_bfe_u32 s16, s17, 0x100003
	s_cmp_lt_u32 s16, 12
	s_cselect_b32 s16, 8, 18
	s_cmpk_gt_i32 s13, 0x4f
	s_cselect_b32 s13, s16, 0
	s_lshl_b32 s16, s64, 2
	s_lshl_b32 s14, s14, 10
	s_and_b32 s16, s16, 0x380
	s_or_b32 s14, s14, s16
	v_writelane_b32 v253, s14, 18
	s_lshl_b32 s14, 2, s19
	v_writelane_b32 v253, s14, 19
	s_lshl_b32 s14, s19, 15
	s_add_i32 s28, s13, s15
	s_lshl_b32 s13, s64, 5
	v_writelane_b32 v253, s14, 20
	s_lshl_b32 s14, s19, 7
	s_and_b32 s16, s13, 0xffffff80
	s_and_b32 s13, s13, 0xf80
	v_writelane_b32 v253, s14, 21
	s_lshl_b32 s14, s19, 8
	s_add_u32 s14, s3, s14
	v_writelane_b32 v253, s19, 22
	s_addc_u32 s15, s20, 0
	v_writelane_b32 v253, s14, 23
	s_nop 1
	v_writelane_b32 v253, s15, 24
	s_sub_i32 s14, 14, s13
	v_writelane_b32 v253, s14, 25
	s_or_b32 s13, s13, 1
	v_writelane_b32 v253, s13, 26
	s_xor_b32 s13, s64, 3
	s_and_b32 s14, s13, 3
	s_lshl_b32 s17, 2, s14
	v_writelane_b32 v253, s17, 27
	s_lshl_b32 s17, s14, 15
	v_writelane_b32 v253, s17, 28
	s_lshl_b32 s17, s14, 7
	s_lshl_b32 s13, s13, 5
	v_writelane_b32 v253, s17, 29
	s_and_b32 s15, s13, 0xffffff80
	v_writelane_b32 v253, s16, 30
	s_add_i32 s16, s16, -15
	s_and_b32 s13, s13, 0xf80
	s_lshl_b32 s14, s14, 8
	v_writelane_b32 v253, s16, 31
	s_add_i32 s16, s15, 0x2000
	v_writelane_b32 v253, s16, 32
	s_add_u32 s16, s3, s14
	s_addc_u32 s17, s20, 0
	s_add_i32 s11, s12, s11
	s_ashr_i32 s12, s11, 31
	s_lshr_b32 s12, s12, 27
	s_add_i32 s12, s11, s12
	v_writelane_b32 v253, s3, 33
	s_and_b32 s14, s12, 0xffe0
	v_writelane_b32 v253, s20, 34
	s_sub_i32 s11, s11, s14
	v_writelane_b32 v253, s16, 35
	s_bfe_i32 s14, s11, 0x80000
	s_bfe_u32 s14, s14, 0x3000c
	v_writelane_b32 v253, s17, 36
	s_add_i32 s3, s15, 0x1ff1
	s_add_i32 s14, s11, s14
	v_writelane_b32 v253, s3, 37
	s_sub_i32 s3, 14, s13
	v_writelane_b32 v253, s3, 38
	s_or_b32 s3, s13, 1
	s_bfe_i32 s13, s14, 0x80000
	s_sext_i32_i16 s13, s13
	v_writelane_b32 v253, s3, 39
	s_ashr_i32 s3, s13, 3
	s_and_b32 s16, s14, 0xf8
	v_writelane_b32 v253, s3, 40
	s_mov_b32 s14, s18
	v_writelane_b32 v253, s14, 41
	s_sub_i32 s11, s11, s16
	s_ashr_i32 s12, s12, 5
	v_writelane_b32 v253, s15, 42
	s_mov_b32 s16, s28
	s_lshl_b32 s12, s12, 3
	s_sext_i32_i8 s11, s11
	s_ashr_i32 s19, s18, 31
	s_ashr_i32 s29, s28, 31
	v_writelane_b32 v253, s16, 43
	s_add_i32 s20, s12, s11
	s_lshr_b32 s12, s13, 3
	s_lshl_b64 s[14:15], s[18:19], 19
	v_writelane_b32 v253, s17, 44
	s_lshl_b64 s[16:17], s[28:29], 19
	s_add_u32 s14, s36, s14
	v_writelane_b32 v253, s16, 45
	s_addc_u32 s15, s37, s15
	s_mul_i32 s13, s20, 0x540000
	v_writelane_b32 v253, s17, 46
	s_add_u32 s16, s14, 0x40000
	v_writelane_b32 v253, s14, 47
	s_addc_u32 s17, s15, 0
	s_ashr_i32 s21, s20, 31
	v_writelane_b32 v253, s15, 48
	s_mul_hi_i32 s11, s20, 0x540000
	s_add_u32 s14, s42, s13
	v_writelane_b32 v253, s16, 49
	s_addc_u32 s15, s43, s11
	s_bfe_i64 s[12:13], s[12:13], 0x100000
	v_writelane_b32 v253, s17, 50
	s_lshl_b64 s[16:17], s[12:13], 18
	v_writelane_b32 v253, s16, 51
	s_mov_b32 s29, 0
	s_nop 0
	v_writelane_b32 v253, s17, 52
	s_add_u32 s16, s14, 0x2a0000
	v_writelane_b32 v253, s14, 53
	s_addc_u32 s17, s15, 0
	s_lshl_b64 s[12:13], s[12:13], 19
	v_writelane_b32 v253, s15, 54
	v_writelane_b32 v253, s16, 55
	s_nop 1
	v_writelane_b32 v253, s17, 56
	v_writelane_b32 v253, s12, 57
	s_nop 1
	v_writelane_b32 v253, s13, 58
	s_mov_b32 s12, s20
	v_writelane_b32 v253, s12, 59
	s_nop 1
	v_writelane_b32 v253, s13, 60
	s_lshl_b64 s[12:13], s[20:21], 19
	s_add_u32 s12, s4, s12
	v_writelane_b32 v253, s4, 61
	s_addc_u32 s13, s5, s13
	s_nop 0
	v_writelane_b32 v253, s5, 62
	s_add_u32 s4, s12, 0x40000
	v_writelane_b32 v253, s12, 63
	s_addc_u32 s5, s13, 0
	s_abs_i32 s11, s26
	v_cvt_f32_u32_e32 v0, s11
	v_writelane_b32 v254, s13, 0
	s_sub_i32 s12, 0, s11
	v_writelane_b32 v254, s4, 1
	v_rcp_iflag_f32_e32 v0, v0
	s_nop 0
	v_writelane_b32 v254, s5, 2
	v_mul_f32_e32 v0, 0x4f7ffffe, v0
	v_cvt_u32_f32_e32 v0, v0
	s_nop 0
	v_readfirstlane_b32 s13, v0
	s_mul_i32 s12, s12, s13
	s_mul_hi_u32 s12, s13, s12
	s_add_i32 s13, s13, s12
	s_abs_i32 s12, s10
	s_mul_hi_u32 s14, s12, s13
	s_mul_i32 s14, s14, s11
	s_sub_i32 s12, s12, s14
	s_ashr_i32 s10, s10, 31
	s_sub_i32 s14, s12, s11
	s_cmp_ge_u32 s12, s11
	s_cselect_b32 s12, s14, s12
	s_sub_i32 s14, s12, s11
	s_cmp_ge_u32 s12, s11
	s_cselect_b32 s12, s14, s12
	s_xor_b32 s12, s12, s10
	s_sub_i32 s3, s12, s10
	s_cmp_lt_i32 s3, 64
	s_cselect_b64 s[4:5], -1, 0
	v_writelane_b32 v254, s4, 3
	s_mul_hi_u32 s12, s13, 0x680
	s_mul_i32 s13, s12, s11
	v_writelane_b32 v254, s5, 4
	s_ashr_i32 s4, s3, 31
	s_lshr_b32 s10, s4, 29
	s_add_i32 s10, s3, s10
	v_writelane_b32 v254, s4, 5
	s_ashr_i32 s4, s10, 3
	s_and_b32 s10, s10, -8
	s_sub_i32 s10, s3, s10
	s_cmp_gt_i32 s10, -1
	v_writelane_b32 v254, s4, 6
	s_cselect_b64 s[4:5], -1, 0
	s_sub_i32 s13, 0x680, s13
	v_writelane_b32 v254, s3, 7
	s_lshl_b32 s3, s10, 3
	s_add_i32 s14, s12, 1
	s_sub_i32 s15, s13, s11
	s_cmp_ge_u32 s13, s11
	s_cselect_b32 s12, s14, s12
	s_cselect_b32 s13, s15, s13
	s_add_i32 s14, s12, 1
	s_cmp_ge_u32 s13, s11
	v_writelane_b32 v254, s4, 8
	s_cselect_b32 s11, s14, s12
	s_xor_b32 s11, s11, s95
	v_writelane_b32 v254, s5, 9
	v_writelane_b32 v254, s3, 10
	s_sub_i32 s3, s11, s95
	s_mul_i32 s11, s3, s26
	s_cmpk_lt_i32 s11, 0x680
	s_cselect_b64 s[12:13], -1, 0
	s_and_b64 s[0:1], s[0:1], s[12:13]
	s_cmp_ge_i32 s11, s9
	s_cselect_b64 s[12:13], -1, 0
	s_and_b64 s[0:1], s[0:1], s[12:13]
	v_writelane_b32 v254, s0, 11
	s_mul_i32 s2, s10, 9
	s_nop 0
	v_writelane_b32 v254, s1, 12
	s_abs_i32 s0, s8
	v_cvt_f32_u32_e32 v0, s0
	s_sub_i32 s1, 0, s0
	v_writelane_b32 v254, s3, 13
	v_rcp_iflag_f32_e32 v0, v0
	s_nop 0
	v_mul_f32_e32 v0, 0x4f7ffffe, v0
	v_cvt_u32_f32_e32 v0, v0
	s_nop 0
	v_readfirstlane_b32 s9, v0
	s_mul_i32 s1, s1, s9
	s_mul_hi_u32 s1, s9, s1
	s_add_i32 s9, s9, s1
	s_abs_i32 s1, s64
	s_mul_hi_u32 s9, s1, s9
	s_mul_i32 s12, s9, s0
	s_sub_i32 s1, s1, s12
	s_xor_b32 s12, s64, s8
	s_ashr_i32 s12, s12, 31
	s_add_i32 s13, s9, 1
	s_sub_i32 s14, s1, s0
	s_cmp_ge_u32 s1, s0
	s_cselect_b32 s9, s13, s9
	s_cselect_b32 s1, s14, s1
	s_add_i32 s13, s9, 1
	s_cmp_ge_u32 s1, s0
	s_cselect_b32 s0, s13, s9
	s_xor_b32 s0, s0, s12
	s_sub_i32 s12, s0, s12
	s_mul_i32 s0, s12, s8
	s_sub_i32 s0, s64, s0
	s_ashr_i32 s1, s0, 31
	s_add_u32 s0, s11, s0
	s_mul_hi_i32 s8, s3, s26
	s_addc_u32 s1, s8, s1
	s_ashr_i32 s8, s0, 31
	s_lshr_b32 s8, s8, 29
	s_add_i32 s8, s0, s8
	s_ashr_i32 s9, s8, 3
	s_and_b32 s8, s8, -8
	s_sub_i32 s8, s0, s8
	s_cmp_lt_i32 s8, 0
	s_cselect_b32 s11, s6, 0xd0
	s_mul_i32 s8, s8, s11
	s_add_i32 s8, s8, s9
	s_mul_hi_i32 s9, s8, 0x4ec4ec4f
	s_lshr_b32 s11, s9, 31
	s_ashr_i32 s9, s9, 6
	s_add_i32 s9, s9, s11
	s_mul_i32 s11, s9, 0xd0
	s_lshl_b32 s9, s9, 3
	s_sub_i32 s8, s8, s11
	s_sub_i32 s11, 64, s9
	s_min_i32 s11, s11, 8
	s_abs_i32 s13, s11
	v_cvt_f32_u32_e32 v0, s13
	s_sub_i32 s14, 0, s13
	s_mov_b32 s6, 0x3f35f0e3
	v_rcp_iflag_f32_e32 v0, v0
	s_nop 0
	v_mul_f32_e32 v0, 0x4f7ffffe, v0
	v_cvt_u32_f32_e32 v0, v0
	s_nop 0
	v_readfirstlane_b32 s15, v0
	s_mul_i32 s14, s14, s15
	s_mul_hi_u32 s14, s15, s14
	s_add_i32 s15, s15, s14
	s_abs_i32 s14, s8
	s_mul_hi_u32 s15, s14, s15
	s_mul_i32 s16, s15, s13
	s_sub_i32 s14, s14, s16
	s_xor_b32 s16, s8, s11
	s_ashr_i32 s16, s16, 31
	s_add_i32 s17, s15, 1
	s_sub_i32 s18, s14, s13
	s_cmp_ge_u32 s14, s13
	s_cselect_b32 s15, s17, s15
	s_cselect_b32 s14, s18, s14
	s_add_i32 s17, s15, 1
	s_cmp_ge_u32 s14, s13
	s_cselect_b32 s13, s17, s15
	s_xor_b32 s13, s13, s16
	s_sub_i32 s13, s13, s16
	s_mul_i32 s11, s13, s11
	s_sub_i32 s8, s8, s11
	s_add_i32 s8, s9, s8
	s_cmp_lt_u32 s13, 18
	s_cselect_b32 s9, 12, 16
	s_cmp_gt_i32 s13, 7
	s_cselect_b32 s9, s9, 10
	s_add_i32 s14, s9, s13
	s_ashr_i32 s13, s12, 31
	s_ashr_i32 s9, s8, 31
	s_lshl_b32 s11, s12, 7
	s_lshl_b64 s[12:13], s[12:13], 17
	s_lshl_b64 s[16:17], s[8:9], 18
	s_add_u32 s9, s40, s16
	s_addc_u32 s16, s41, s17
	s_ashr_i32 s15, s14, 31
	s_lshl_b64 s[4:5], s[14:15], 18
	v_writelane_b32 v254, s4, 14
	v_mov_b64_e32 v[0:1], 0x680
	v_cmp_lt_i64_e64 s[0:1], s[0:1], v[0:1]
	v_writelane_b32 v254, s5, 15
	s_add_u32 s4, s9, s12
	s_addc_u32 s5, s16, s13
	s_add_u32 s12, s4, 0x20000
	s_addc_u32 s13, s5, 0
	v_writelane_b32 v254, s12, 16
	s_nop 1
	v_writelane_b32 v254, s13, 17
	s_add_u32 s12, s4, 0x20080
	s_addc_u32 s13, s5, 0
	v_writelane_b32 v254, s12, 18
	s_nop 1
	v_writelane_b32 v254, s13, 19
	s_add_u32 s12, s4, 0x20100
	s_addc_u32 s13, s5, 0
	v_writelane_b32 v254, s12, 20
	s_nop 1
	v_writelane_b32 v254, s13, 21
	s_add_u32 s12, s4, 0x20180
	s_addc_u32 s13, s5, 0
	v_writelane_b32 v254, s12, 22
	s_nop 1
	v_writelane_b32 v254, s13, 23
	s_add_u32 s12, s4, 0x20200
	s_addc_u32 s13, s5, 0
	v_writelane_b32 v254, s12, 24
	s_nop 1
	v_writelane_b32 v254, s13, 25
	s_add_u32 s12, s4, 0x20280
	s_addc_u32 s13, s5, 0
	v_writelane_b32 v254, s12, 26
	s_nop 1
	v_writelane_b32 v254, s13, 27
	s_add_u32 s12, s4, 0x20300
	s_addc_u32 s13, s5, 0
	v_writelane_b32 v254, s12, 28
	s_nop 1
	v_writelane_b32 v254, s13, 29
	s_add_u32 s12, s4, 0x20380
	v_writelane_b32 v254, s4, 30
	s_addc_u32 s13, s5, 0
	s_lshl_b32 s8, s8, 8
	v_writelane_b32 v254, s5, 31
	v_writelane_b32 v254, s12, 32
	s_add_i32 s3, s11, s8
	s_nop 0
	v_writelane_b32 v254, s13, 33
	v_writelane_b32 v254, s3, 34
	s_lshl_b32 s3, s14, 8
	s_cmp_gt_i32 s14, 3
	v_writelane_b32 v254, s3, 35
	s_cselect_b64 s[4:5], -1, 0
	v_writelane_b32 v254, s4, 36
	s_cmp_gt_u32 s14, 5
	s_brev_b32 s3, 64
	v_writelane_b32 v254, s5, 37
	s_cselect_b64 s[4:5], -1, 0
	v_writelane_b32 v254, s4, 38
	s_cmp_gt_u32 s14, 7
	s_nop 0
	v_writelane_b32 v254, s5, 39
	s_cselect_b64 s[4:5], -1, 0
	v_writelane_b32 v254, s4, 40
	s_cmp_gt_u32 s14, 9
	s_nop 0
	v_writelane_b32 v254, s5, 41
	s_cselect_b64 s[4:5], -1, 0
	v_writelane_b32 v254, s4, 42
	s_cmp_gt_u32 s14, 15
	s_nop 0
	v_writelane_b32 v254, s5, 43
	s_cselect_b64 s[4:5], -1, 0
	v_writelane_b32 v254, s4, 44
	s_cmp_lt_u32 s14, 26
	s_cselect_b32 s8, 2, 3
	v_writelane_b32 v254, s5, 45
	s_cmp_gt_u32 s14, 23
	s_cselect_b32 s8, s8, 4
	s_cmp_gt_u32 s14, 21
	v_writelane_b32 v254, s2, 46
	s_cselect_b32 s8, s8, 2
	s_cmp_gt_u32 s14, 19
	v_writelane_b32 v254, s0, 47
	s_mov_b32 s5, 0xf800000
	s_mov_b32 s4, 0x3b808081
	v_writelane_b32 v254, s1, 48
	s_cselect_b32 s0, s8, 0
	v_writelane_b32 v254, s0, 49
	s_lshl_b32 s0, s26, 10
	v_writelane_b32 v254, s0, 50
	s_lshl_b32 s0, s26, 11
	v_writelane_b32 v254, s0, 51
	s_lshl_b32 s0, s64, 12
	v_writelane_b32 v254, s0, 52
	s_lshl_b32 s0, s26, 15
	v_writelane_b32 v254, s0, 53
	s_add_i32 s0, 0, 0x23fc0
	v_writelane_b32 v254, s0, 54
	s_add_i32 s0, 0, 0x23fc4
	v_writelane_b32 v254, s0, 55
	s_add_i32 s0, 0, 0xff0
	v_writelane_b32 v254, s0, 56
	v_writelane_b32 v254, s47, 57
	v_writelane_b32 v254, s95, 58
	v_writelane_b32 v254, s86, 59
	s_movk_i32 s1, 0x2000
	s_add_i32 s27, 0, 0x11000
	v_writelane_b32 v254, s87, 60
	v_writelane_b32 v254, s84, 61
	s_mov_b32 s0, 0xbe11a98e
	s_mov_b32 s2, s29
	v_writelane_b32 v254, s85, 62
	v_writelane_b32 v254, s88, 63
	s_nop 1
	v_writelane_b32 v255, s89, 0
	v_writelane_b32 v255, s83, 1
	s_branch .LBB0_177

.LBB0_208:
	s_add_i32 s87, s87, 1
	s_cmp_ge_i32 s87, s76
	s_mov_b64 s[66:67], 0
	s_cbranch_scc1 .LBB0_211
	s_lshl_b32 s14, s87, 2
	s_lshr_b32 s14, 0x6521340, s14
	s_and_b32 s14, s14, 15
	s_mul_i32 s8, s14, s95
	s_mul_hi_u32 s9, s14, s26
	s_add_i32 s9, s9, s8
	s_mul_i32 s8, s14, s26
	s_add_u32 s14, s8, s64
	s_addc_u32 s15, s9, s7
	v_mov_b64_e32 v[0:1], 0x67f
	v_cmp_gt_i64_e32 vcc, s[14:15], v[0:1]
	s_cbranch_vccnz .LBB0_211
	s_ashr_i32 s8, s14, 31
	s_lshr_b32 s8, s8, 29
	s_add_i32 s8, s14, s8
	s_ashr_i32 s9, s8, 3
	s_and_b32 s8, s8, -8
	s_sub_i32 s8, s14, s8
	s_cmp_lt_i32 s8, 0
	s_movk_i32 s14, 0xd1
	s_cselect_b32 s14, s14, 0xd0
	s_mul_i32 s8, s8, s14
	s_add_i32 s8, s8, s9
	s_mul_hi_i32 s9, s8, 0x4ec4ec4f
	s_lshr_b32 s14, s9, 31
	s_ashr_i32 s9, s9, 6
	s_add_i32 s9, s9, s14
	s_lshl_b32 s14, s9, 3
	s_sub_i32 s15, 64, s14
	s_min_i32 s15, s15, 8
	s_abs_i32 s30, s15
	v_cvt_f32_u32_e32 v0, s30
	s_sub_i32 s34, 0, s30
	s_mulk_i32 s9, 0xd0
	s_sub_i32 s8, s8, s9
	v_rcp_iflag_f32_e32 v0, v0
	s_abs_i32 s9, s8
	s_xor_b32 s31, s8, s15
	s_ashr_i32 s31, s31, 31
	v_mul_f32_e32 v0, 0x4f7ffffe, v0
	v_cvt_u32_f32_e32 v0, v0
	s_mov_b64 s[66:67], -1
	v_readfirstlane_b32 s35, v0
	s_mul_i32 s34, s34, s35
	s_mul_hi_u32 s34, s35, s34
	s_add_i32 s35, s35, s34
	s_mul_hi_u32 s34, s9, s35
	s_mul_i32 s35, s34, s30
	s_sub_i32 s9, s9, s35
	s_add_i32 s44, s34, 1
	s_sub_i32 s35, s9, s30
	s_cmp_ge_u32 s9, s30
	s_cselect_b32 s34, s44, s34
	s_cselect_b32 s9, s35, s9
	s_add_i32 s35, s34, 1
	s_cmp_ge_u32 s9, s30
	s_cselect_b32 s9, s35, s34
	s_xor_b32 s9, s9, s31
	s_sub_i32 s9, s9, s31
	s_mul_i32 s15, s9, s15
	s_sub_i32 s8, s8, s15
	s_add_i32 s30, s14, s8
	s_cmp_lt_u32 s9, 18
	s_cselect_b32 s8, 12, 16
	s_cmp_gt_i32 s9, 7
	s_cselect_b32 s8, s8, 10
	s_cmp_lt_u32 s9, 4
	s_cselect_b32 s8, 36, s8
	s_sub_u32 s14, s9, 20
	s_cmp_lt_u32 s14, 4
	s_cselect_b32 s8, 0xfffffff6, s8
	s_add_i32 s34, s8, s9
